# in-proj phase start: the 1-3 us per-class stagger skipped (re-test on the current K-loop)
# speedup vs baseline: 1.0015x; 1.0012x over previous
; __device__ __forceinline__ void stagger(const Frame& F) {
;     const int cls = ((F.bid >> 3) % STAG_N) >> 1;
;     if (cls) { const unsigned long long t0 = __builtin_amdgcn_s_memrealtime(); while (__builtin_amdgcn_s_memrealtime() - t0 < (unsigned long long)(cls * STAG_TICKS)) __builtin_amdgcn_s_sleep(8); }
; }
; __global__ void __launch_bounds__(512, 2) mk_fwd(Args args) {
;     ...
;         else { const int l = (ph - 1) >> 2, s = (ph - 1) & 3;
;             if (s == 0) p1_inproj(F, l);
.LBB0_122:
	s_andn2_b64 vcc, exec, s[2:3]
	s_cbranch_vccnz .LBB0_515
	v_writelane_b32 v255, s93, 36
	v_writelane_b32 v255, s52, 26
	s_cmp_eq_u32 s8, 1
	s_mov_b64 s[2:3], -1
	v_writelane_b32 v255, s53, 27
	v_writelane_b32 v255, s54, 28
	v_writelane_b32 v255, s55, 29
	s_cbranch_scc1 .LBB0_346
	s_ashr_i32 s2, s65, 3
	s_lshr_b32 s3, s2, 29
	s_add_i32 s3, s2, s3
	s_and_b32 s3, s3, -8
	s_sub_i32 s4, s2, s3
	s_cmp_lt_u32 s4, 2
	s_branch .LBB0_127
	s_memrealtime s[2:3]
	s_memrealtime s[6:7]
	s_lshr_b32 s4, s4, 1
	s_mulk_i32 s4, 0x64
	s_ashr_i32 s5, s4, 31
	s_waitcnt vmcnt(7)
	v_mov_b64_e32 v[2:3], s[4:5]
	s_waitcnt lgkmcnt(0)
	s_sub_u32 s6, s6, s2
	s_subb_u32 s7, s7, s3
	v_cmp_ge_u64_e32 vcc, s[6:7], v[2:3]
	s_cbranch_vccnz .LBB0_127
